# speedup vs baseline: 1.0100x; 1.0100x over previous
; DEVI float logsigmoid(float z) { return fminf(z, 0.f) - __logf(1.f + __expf(-fabsf(z))); }
; DEVI void phase_gla_prep(const Params& p, bf16* shm) {
;     ...
;   const int tid = threadIdx.x, wave = tid >> 6, lane = tid & 63, fr = lane & 15, fq = lane >> 4;
;   const int dk = tid & 255, half = tid >> 8;
;   for (int item = blockIdx.x; item < 2048; item += gridDim.x) {
;     const int n = item & 127, h = (item >> 7) & 3, b = item >> 9;
;     const long t0 = (long)b * SEQ + n * 64;
;     for (int i = tid; i < 64 * 16; i += 512) GKs[i] = GK[t0 * 16 + i];
;     float wu[16];
; #pragma unroll
;     for (int r = 0; r < 16; ++r) wu[r] = wup[r * 1024 + h * 256 + dk];
;     const float bg = bgk[h * 256 + dk];
;     __syncthreads();
;     float part = 0.f;
;     for (int s = half * 32; s < half * 32 + 32; ++s) {
;       float z = bg;
; #pragma unroll
;       for (int r = 0; r < 16; ++r) z += GKs[s * 16 + r] * wu[r];
;       part += logsigmoid(z) * (1.f / 16.f);
;     }
;     hs[half * 256 + dk] = part;
;     __syncthreads();
;     const float blast = hs[dk] + hs[256 + dk];
;     float run = half ? hs[dk] : 0.f;
;     const int ks_ = dk >> 5, l = dk & 31;
;     const int pos = ks_ * 32 + ((l & 15) >> 2) * 8 + (l >> 4) * 4 + (l & 3);
;     ...
; #pragma unroll
;     for (int i = 0; i < 4; ++i) {
;       int ch = tid + i * 512; int row = ch >> 3, seg = (ch & 7) * 8;
;       *reinterpret_cast<uint4*>(KT + ((long)item * 256 + row) * 64 + seg) = *reinterpret_cast<const uint4*>(&Tt[row * 72 + seg]);
;     }
;     {
;       const int ti = wave >> 1;
; #pragma unroll
;       for (int u = 0; u < 2; ++u) {
;         const int sj = (wave & 1) * 2 + u;
;         f32x4 acc = {0.f, 0.f, 0.f, 0.f};
; #pragma unroll
;         for (int ks = 0; ks < 8; ++ks) {
;           bf16x8 av = *reinterpret_cast<const bf16x8*>(&Ks[(sj * 16 + fr) * 264 + ks * 32 + fq * 8]);
;           bf16x8 bv = *reinterpret_cast<const bf16x8*>(&Qs[(ti * 16 + fr) * 264 + ks * 32 + fq * 8]);
;           acc = __builtin_amdgcn_mfma_f32_16x16x32_bf16(av, bv, acc, 0, 0, 0);
;         }
;         const int t = ti * 16 + fr, s0 = sj * 16 + fq * 4;
;         float r[4];
; #pragma unroll
;         for (int j = 0; j < 4; ++j) r[j] = (s0 + j <= t) ? acc[j] : 0.f;
;         uint2 o; o.x = pack2(r[0], r[1]); o.y = pack2(r[2], r[3]);
;         *reinterpret_cast<uint2*>(SC + ((long)item * 64 + t) * 64 + s0) = o;
.LBB0_1497:
	s_cmp_gt_i32 s30, 15
	s_cselect_b64 s[0:1], -1, 0
	s_cmp_lt_i32 s31, 16
	s_cselect_b64 s[2:3], -1, 0
	s_or_b64 s[0:1], s[0:1], s[2:3]
	s_and_b64 vcc, exec, s[0:1]
	s_cbranch_vccnz .LBB0_1522
	s_cmpk_gt_i32 s92, 0x7ff
	s_waitcnt lgkmcnt(0)
	v_and_b32_e32 v3, 0x3ff, v0
	s_cbranch_scc1 .LBB0_1513
	v_lshrrev_b32_e32 v2, 3, v3
	v_and_b32_e32 v9, 0xff, v3
	v_bfe_u32 v8, v3, 4, 2
	v_and_b32_e32 v4, 0x60, v2
	v_mul_u32_u24_e32 v10, 0x90, v9
	s_add_i32 s2, 0, 0x12000
	v_lshlrev_b32_e32 v12, 4, v3
	v_lshl_add_u32 v35, v8, 4, 0
	v_lshlrev_b32_e32 v14, 2, v8
	v_lshlrev_b32_e32 v8, 1, v4
	v_and_b32_e32 v20, 0x70, v12
	v_add3_u32 v92, s2, v10, v8
	v_add_u32_e32 v8, 0x200, v3
	v_add_u32_e32 v12, 0x600, v3
	s_movk_i32 s18, 0x90
	v_add_u32_e32 v13, s2, v20
	v_lshrrev_b32_e32 v8, 3, v8
	v_lshrrev_b32_e32 v12, 3, v12
	v_lshrrev_b32_e32 v93, 8, v3
	v_lshlrev_b32_e32 v93, 5, v93
	v_bfe_u32 v94, v3, 7, 1
	v_lshl_or_b32 v93, v94, 4, v93
	v_and_b32_e32 v94, 15, v3
	v_or_b32_e32 v93, v93, v94
	v_mul_u32_u24_e32 v93, 0x90, v93
	v_bfe_u32 v94, v3, 6, 1
	v_bfe_u32 v96, v3, 4, 2
	v_lshl_or_b32 v94, v94, 2, v96
	v_lshl_add_u32 v93, v94, 4, v93
	v_add_u32_e32 v93, s2, v93
	v_add_u32_e32 v94, 0x2400, v93
	v_add_u32_e32 v96, 0x6c00, v93
	v_lshrrev_b32_e32 v13, 1, v3
	v_and_b32_e32 v6, 15, v3
	v_and_b32_e32 v13, 32, v13
	s_movk_i32 s3, 0x70
	v_or_b32_e32 v15, v13, v6
	v_or_b32_e32 v42, v14, v13
	v_or_b32_e32 v13, 16, v13
	v_and_or_b32 v22, v2, s3, v6
	v_or_b32_e32 v6, v13, v6
	v_mul_u32_u24_e32 v39, 0x210, v6
	v_or_b32_e32 v6, v13, v14
	v_cmp_gt_u32_e64 s[10:11], v6, v22
	v_cmp_lt_u32_e64 s[12:13], v6, v22
	v_or_b32_e32 v13, 2, v6
	v_or_b32_e32 v6, 3, v6
	v_cmp_gt_u32_e64 s[16:17], v6, v22
	v_lshlrev_b32_e32 v6, 1, v3
	v_and_b32_e32 v32, 24, v6
	v_lshrrev_b32_e32 v6, 2, v3
	v_mov_b32_e32 v7, 0
	v_mul_u32_u24_e32 v37, 0x210, v15
	v_or_b32_e32 v15, 2, v42
	v_and_b32_e32 v41, 4, v6
	v_lshlrev_b32_e32 v6, 1, v9
	v_cmp_gt_u32_e64 s[6:7], v15, v22
	v_or_b32_e32 v15, 3, v42
	v_lshl_add_u64 v[24:25], s[28:29], 0, v[6:7]
	s_mov_b64 s[20:21], 0xf000000
	v_lshlrev_b32_e32 v18, 2, v9
	v_cmp_gt_u32_e64 s[8:9], v15, v22
	v_lshl_add_u64 v[14:15], v[24:25], 0, s[20:21]
	s_mov_b64 s[20:21], 0x13000000
	v_mov_b32_e32 v19, v7
	v_add_u32_e32 v90, 0, v18
	s_movk_i32 s3, 0x210
	v_lshl_add_u64 v[16:17], v[24:25], 0, s[20:21]
	v_lshl_add_u64 v[18:19], s[28:29], 0, v[18:19]
	s_mov_b64 s[20:21], 0x34200000
	v_mov_b32_e32 v21, v7
	v_mad_u32_u24 v91, v22, s3, v35
	v_cmp_gt_u32_e64 s[2:3], v42, v22
	v_cmp_lt_u32_e64 s[4:5], v42, v22
	v_cmp_gt_u32_e64 s[14:15], v13, v22
	v_lshl_add_u64 v[18:19], v[18:19], 0, s[20:21]
	v_lshl_add_u64 v[26:27], s[28:29], 0, v[20:21]
	s_mov_b64 s[20:21], 0x27200000
	v_lshrrev_b32_e32 v22, 7, v3
	v_lshlrev_b32_e32 v22, 11, v22
	v_and_b32_e32 v23, 15, v3
	v_lshl_or_b32 v22, v23, 4, v22
	v_mov_b32_e32 v23, v7
	v_and_b32_e32 v33, 0xe3, v3
	v_lshl_add_u64 v[20:21], v[26:27], 0, s[20:21]
	v_lshl_add_u64 v[22:23], s[28:29], 0, v[22:23]
	s_mov_b64 s[20:21], 0x33200000
	v_lshl_add_u64 v[22:23], v[22:23], 0, s[20:21]
	s_mov_b64 s[20:21], 0x17000000
	v_lshrrev_b32_e32 v43, 8, v3
	v_or3_b32 v32, v33, v32, v41
	v_lshlrev_b32_e32 v28, 2, v3
	v_lshl_add_u64 v[24:25], v[24:25], 0, s[20:21]
	s_mov_b64 s[20:21], 0x2b200000
	v_mov_b32_e32 v29, v7
	v_lshlrev_b32_e32 v32, 1, v32
	v_mul_u32_u24_e32 v41, 0x4200, v43
	v_add_u32_e32 v11, 0, v28
	v_or_b32_e32 v30, 31, v2
	v_or_b32_e32 v10, 0x80, v2
	v_lshl_add_u64 v[26:27], v[26:27], 0, s[20:21]
	v_lshl_add_u64 v[28:29], s[28:29], 0, v[28:29]
	s_mov_b64 s[20:21], 0x27000000
	v_lshl_or_b32 v32, v43, 14, v32
	v_mov_b32_e32 v33, v7
	v_or_b32_e32 v6, v41, v6
	s_movk_i32 s0, 0x100
	v_lshlrev_b32_e32 v34, 6, v2
	v_lshlrev_b32_e32 v36, 6, v8
	v_lshlrev_b32_e32 v38, 6, v10
	v_lshlrev_b32_e32 v40, 6, v12
	v_lshl_add_u64 v[28:29], v[28:29], 0, s[20:21]
	v_sub_u32_e32 v30, v30, v4
	v_lshlrev_b32_e32 v99, 11, v43
	v_lshl_add_u64 v[32:33], s[28:29], 0, v[32:33]
	s_mov_b64 s[20:21], 0x34400800
	v_add_u32_e32 v101, 0x1800, v6
	v_lshlrev_b32_e32 v6, 6, v43
	s_mov_b32 s19, 0
	v_cmp_gt_u32_e64 s[0:1], s0, v3
	v_mov_b32_e32 v5, v7
	v_add_u32_e32 v95, 0x4800, v93
	v_mov_b32_e32 v13, v7
	v_add_u32_e32 v97, 0xfffffe00, v3
	s_lshl_b32 s70, s92, 6
	s_lshl_b32 s71, s33, 6
	v_add_u32_e32 v98, 1, v30
	v_add_u32_e32 v100, 0, v99
	v_lshlrev_b32_e32 v30, 15, v43
	v_mov_b32_e32 v31, v7
	v_lshl_add_u64 v[32:33], v[32:33], 0, s[20:21]
	v_mad_u32_u24 v102, v9, s18, v6
	s_mov_b64 s[22:23], 0x800
	s_mov_b32 s72, 0xbfb8aa3b
	s_mov_b32 s73, 0x800000
	s_mov_b32 s74, 0x3f317217
	s_mov_b32 s75, 0x7f800000
	s_brev_b32 s76, 63
	s_mov_b64 s[56:57], 0x4000
	s_mov_b64 s[58:59], 0x1000
	v_lshlrev_b32_e32 v6, 1, v34
	v_lshlrev_b32_e32 v34, 1, v36
	v_lshlrev_b32_e32 v36, 1, v38
	v_lshlrev_b32_e32 v38, 1, v40
	v_add_u32_e32 v103, v35, v37
	v_bfe_u32 v40, v3, 6, 1
	v_lshlrev_b32_e32 v40, 10, v40
	v_bfe_u32 v105, v3, 5, 1
	v_lshl_or_b32 v40, v105, 8, v40
	v_bfe_u32 v105, v3, 4, 1
	v_lshl_or_b32 v40, v105, 3, v40
	s_mov_b32 s77, 0x5040100
	v_add_u32_e32 v104, v35, v39
	v_mov_b32_e32 v105, 0x41b17218
	s_mov_b32 s60, s92

; DEVI void phase_gla_prep(const Params& p, bf16* shm) {
;     ...
; #pragma unroll
;     for (int i = 0; i < 4; ++i) {
;       int ch = tid + i * 512; int row = ch >> 3, seg = (ch & 7) * 8;
;       *reinterpret_cast<uint4*>(KT + ((long)item * 256 + row) * 64 + seg) = *reinterpret_cast<const uint4*>(&Tt[row * 72 + seg]);
;     }
;     {
;       const int ti = wave >> 1;
; #pragma unroll
;       for (int u = 0; u < 2; ++u) {
;         const int sj = (wave & 1) * 2 + u;
;         f32x4 acc = {0.f, 0.f, 0.f, 0.f};
; #pragma unroll
;         for (int ks = 0; ks < 8; ++ks) {
;           bf16x8 av = *reinterpret_cast<const bf16x8*>(&Ks[(sj * 16 + fr) * 264 + ks * 32 + fq * 8]);
;           bf16x8 bv = *reinterpret_cast<const bf16x8*>(&Qs[(ti * 16 + fr) * 264 + ks * 32 + fq * 8]);
;           acc = __builtin_amdgcn_mfma_f32_16x16x32_bf16(av, bv, acc, 0, 0, 0);
;         }
;         const int t = ti * 16 + fr, s0 = sj * 16 + fq * 4;
;         float r[4];
; #pragma unroll
;         for (int j = 0; j < 4; ++j) r[j] = (s0 + j <= t) ? acc[j] : 0.f;
;         uint2 o; o.x = pack2(r[0], r[1]); o.y = pack2(r[2], r[3]);
;         *reinterpret_cast<uint2*>(SC + ((long)item * 64 + t) * 64 + s0) = o;
;       }
.LBB0_1508:
	s_or_b64 exec, exec, s[20:21]
	s_waitcnt lgkmcnt(0)
	s_barrier
	ds_read_b128 v[44:47], v103 offset:39936
	ds_read_b128 v[48:51], v93
	v_lshl_add_u64 v[88:89], v[20:21], 0, s[62:63]
	ds_read_b128 v[52:55], v91 offset:6144
	ds_read_b128 v[56:59], v103 offset:40000
	ds_read_b128 v[60:63], v94
	v_lshl_add_u64 v[64:65], v[88:89], 0, v[6:7]
	s_waitcnt lgkmcnt(2)
	v_mfma_f32_16x16x32_bf16 v[44:47], v[44:47], v[52:55], 0
	global_store_dwordx4 v[64:65], v[48:51], off
	ds_read_b128 v[48:51], v91 offset:6208
	ds_read_b128 v[64:67], v103 offset:40064
	ds_read_b128 v[68:71], v91 offset:6272
	ds_read_b128 v[72:75], v103 offset:40128
	s_waitcnt lgkmcnt(3)
	v_mfma_f32_16x16x32_bf16 v[44:47], v[56:59], v[48:51], v[44:47]
	ds_read_b128 v[56:59], v91 offset:6336
	ds_read_b128 v[76:79], v103 offset:40192
	v_mov_b32_e32 v35, v7
	v_lshl_add_u64 v[80:81], v[88:89], 0, v[34:35]
	s_waitcnt lgkmcnt(3)
	v_mfma_f32_16x16x32_bf16 v[44:47], v[64:67], v[68:71], v[44:47]
	global_store_dwordx4 v[80:81], v[60:63], off
	ds_read_b128 v[60:63], v91 offset:6400
	ds_read_b128 v[64:67], v103 offset:40256
	v_mov_b32_e32 v37, v7
	s_waitcnt lgkmcnt(3)
	v_mfma_f32_16x16x32_bf16 v[44:47], v[72:75], v[56:59], v[44:47]
	ds_read_b128 v[72:75], v91 offset:6464
	ds_read_b128 v[80:83], v103 offset:40320
	v_lshl_add_u64 v[114:115], v[88:89], 0, v[36:37]
	v_mov_b32_e32 v39, v7
	s_waitcnt lgkmcnt(3)
	v_mfma_f32_16x16x32_bf16 v[44:47], v[76:79], v[60:63], v[44:47]
	ds_read_b128 v[76:79], v91 offset:6528
	ds_read_b128 v[84:87], v103 offset:40384
	v_lshl_add_u64 v[88:89], v[88:89], 0, v[38:39]
	s_lshl_b64 s[20:21], s[60:61], 13
	s_waitcnt lgkmcnt(3)
	v_mfma_f32_16x16x32_bf16 v[44:47], v[64:67], v[72:75], v[44:47]
	ds_read_b128 v[64:67], v95
	ds_read_b128 v[106:109], v91 offset:6592
	ds_read_b128 v[110:113], v104 offset:39936
	s_lshl_b32 s18, s60, 6
	s_and_b32 s18, s18, 0x1fc0
	s_waitcnt lgkmcnt(4)
	v_mfma_f32_16x16x32_bf16 v[44:47], v[80:83], v[76:79], v[44:47]
	ds_read_b128 v[80:83], v96
	s_waitcnt lgkmcnt(3)
	global_store_dwordx4 v[114:115], v[64:67], off
	ds_read_b128 v[64:67], v104 offset:40000
	s_waitcnt lgkmcnt(3)
	v_mfma_f32_16x16x32_bf16 v[44:47], v[84:87], v[106:109], v[44:47]
	ds_read_b128 v[84:87], v104 offset:40064
	s_waitcnt lgkmcnt(2)
	global_store_dwordx4 v[88:89], v[80:83], off
	ds_read_b128 v[80:83], v104 offset:40128
	v_mfma_f32_16x16x32_bf16 v[52:55], v[110:113], v[52:55], 0
	v_lshl_add_u64 v[88:89], v[22:23], 0, s[20:21]
	s_nop 1
	v_cvt_pk_bf16_f32 v35, v44, s0
	v_cvt_pk_bf16_f32 v37, v45, s0
	s_waitcnt lgkmcnt(2)
	v_mfma_f32_16x16x32_bf16 v[48:51], v[64:67], v[48:51], v[52:55]
	ds_read_b128 v[64:67], v104 offset:40256
	v_cvt_pk_bf16_f32 v39, v46, s0
	v_cvt_pk_bf16_f32 v41, v47, s0
	ds_read_b128 v[52:55], v104 offset:40192
	s_waitcnt lgkmcnt(3)
	v_mfma_f32_16x16x32_bf16 v[48:51], v[84:87], v[68:71], v[48:51]
	ds_read_b128 v[44:47], v104 offset:40384
	v_cndmask_b32_e64 v35, v35, 0, s[2:3]
	v_cndmask_b32_e64 v37, 0, v37, s[4:5]
	s_waitcnt lgkmcnt(3)
	v_mfma_f32_16x16x32_bf16 v[48:51], v[80:83], v[56:59], v[48:51]
	ds_read_b128 v[56:59], v104 offset:40320
	v_cndmask_b32_e64 v39, v39, 0, s[6:7]
	s_or_b32 s64, s64, s18
	s_waitcnt lgkmcnt(2)
	v_mfma_f32_16x16x32_bf16 v[48:51], v[52:55], v[60:63], v[48:51]
	v_cndmask_b32_e64 v54, v41, 0, s[8:9]
	v_mov_b32_e32 v41, v7
	v_lshl_add_u64 v[52:53], v[88:89], 0, v[40:41]
	v_mfma_f32_16x16x32_bf16 v[48:51], v[64:67], v[72:75], v[48:51]
	v_perm_b32 v55, v54, v39, s77
	v_perm_b32 v54, v37, v35, s77
	s_lshl_b32 s18, s34, 10
	s_waitcnt lgkmcnt(0)
	v_mfma_f32_16x16x32_bf16 v[48:51], v[56:59], v[76:79], v[48:51]
	v_lshl_add_u64 v[42:43], s[64:65], 0, v[4:5]
	s_mov_b64 s[20:21], -1
	global_store_dwordx2 v[52:53], v[54:55], off
	v_mfma_f32_16x16x32_bf16 v[44:47], v[44:47], v[106:109], v[48:51]
	s_nop 7
	v_cvt_pk_bf16_f32 v35, v44, s0
	v_cvt_pk_bf16_f32 v37, v45, s0
	v_cvt_pk_bf16_f32 v39, v46, s0
	v_cvt_pk_bf16_f32 v41, v47, s0
	v_cndmask_b32_e64 v35, v35, 0, s[10:11]
	v_cndmask_b32_e64 v37, 0, v37, s[12:13]
	v_cndmask_b32_e64 v39, v39, 0, s[14:15]
	v_cndmask_b32_e64 v41, v41, 0, s[16:17]
	v_perm_b32 v45, v41, v39, s77
	v_perm_b32 v44, v37, v35, s77
	global_store_dwordx2 v[52:53], v[44:45], off offset:512
	v_lshl_add_u64 v[44:45], v[24:25], 0, s[18:19]
	s_mov_b32 s18, 0
	s_barrier

; DEVI void phase_gla_scan(const Params& p, bf16* shm) {
;   int tid_ = threadIdx.x; asm volatile("" : "+v"(tid_));
;   const int wave = tid_ >> 6, lane = tid_ & 63, fr = lane & 15, fq = lane >> 4;
;   const int tbi = wave >> 1, sli = wave & 1;
;   f32x4* part = reinterpret_cast<f32x4*>(shm);
;   __amdgpu_buffer_rsrc_t rq = __builtin_amdgcn_make_buffer_rsrc((void*)(p.ws + G_QI), 0, 0x7fffffff, 0x00020000);
;   __amdgpu_buffer_rsrc_t rk = __builtin_amdgcn_make_buffer_rsrc((void*)(p.ws + G_KT), 0, 0x7fffffff, 0x00020000);
;   __amdgpu_buffer_rsrc_t rv = __builtin_amdgcn_make_buffer_rsrc((void*)(p.ws + G_VT), 0, 0x7fffffff, 0x00020000);
;   __amdgpu_buffer_rsrc_t rs = __builtin_amdgcn_make_buffer_rsrc((void*)(p.ws + G_SC), 0, 0x7fffffff, 0x00020000);
;   __amdgpu_buffer_rsrc_t rd = __builtin_amdgcn_make_buffer_rsrc((void*)(p.ws + G_DV), 0, 0x7fffffff, 0x00020000);
;   __amdgpu_buffer_rsrc_t ro = __builtin_amdgcn_make_buffer_rsrc((void*)(p.ws + G_O), 0, 0x7fffffff, 0x00020000);
;   const int nb = gridDim.x;
;   for (int blk = blockIdx.x; blk < 256; blk += nb) {
;     int bh, pr;
;     if (nb == 256) { const int x = blk & 7, li = blk >> 3; bh = x * 2 + (li >> 4); pr = li & 15; }
;     else { bh = blk >> 4; pr = blk & 15; }
;     const int vsb = pr * 32, b = bh >> 2, h = bh & 3;
;     const int vq = (fr * 256 + wave * 32 + fq * 8) * 2;
;     const int vk = ((wave * 32 + fr) * 64 + fq * 8) * 2;
;     const int vv = ((vsb + fr) * 64 + fq * 8) * 2;
;     const int vsc = ((tbi * 16 + fr) * 64 + fq * 8) * 2;
;     const int vd = (wave * 32 + fq * 4) * 4;
;     const int vo = ((tbi * 16 + fq * 4) * 2048 + h * 512 + vsb + sli * 16 + fr) * 2;
;     const int item0 = bh * 128;
;     const int tok0 = b * SEQ;
.LBB0_1536:
	s_cmp_gt_i32 s30, 16
	s_cselect_b64 s[0:1], -1, 0
	s_cmp_lt_i32 s31, 17
	s_cselect_b64 s[2:3], -1, 0
	s_or_b64 s[0:1], s[0:1], s[2:3]
	s_and_b64 vcc, exec, s[0:1]
	s_cbranch_vccnz .LBB0_1573
	s_load_dword s0, s[84:85], 0x10
	v_and_b32_e32 v164, 0x3ff, v0
	v_mov_b32_e32 v2, v164
	s_waitcnt lgkmcnt(0)
	s_lshr_b32 s0, s0, 16
	s_cmp_lg_u32 s0, 0
	s_cselect_b64 s[0:1], -1, 0
	s_cmp_lg_u64 s[0:1], 0
	s_addc_u32 s34, s33, 0
	s_cmpk_gt_i32 s92, 0xff
	s_cbranch_scc1 .LBB0_1550
	s_add_u32 s4, s28, 0x34400000
	s_addc_u32 s0, s29, 0
	s_and_b32 s5, s0, 0xffff
	s_add_u32 s12, s28, 0x27200000
	s_addc_u32 s0, s29, 0
	s_and_b32 s13, s0, 0xffff
	s_add_u32 s16, s28, 0x2b200000
	s_addc_u32 s0, s29, 0
	s_and_b32 s17, s0, 0xffff
	s_add_u32 s20, s28, 0x33200000
	s_addc_u32 s0, s29, 0
	v_and_b32_e32 v165, 15, v2
	s_and_b32 s21, s0, 0xffff
	v_ashrrev_i32_e32 v4, 6, v2
	v_and_b32_e32 v8, 0xffffffc0, v2
	s_add_u32 s56, s28, 0x34200000
	v_lshlrev_b32_e32 v3, 4, v2
	v_ashrrev_i32_e32 v6, 7, v2
	v_lshlrev_b32_e32 v7, 5, v4
	v_and_b32_e32 v167, 48, v2
	v_lshl_add_u32 v8, v165, 9, v8
	v_lshrrev_b32_e32 v2, 2, v2
	s_addc_u32 s0, s29, 0
	v_or_b32_e32 v168, v8, v167
	v_or_b32_e32 v8, v7, v165
	v_and_b32_e32 v2, 12, v2
	s_and_b32 s57, s0, 0xffff
	v_and_b32_e32 v5, 1, v4
	v_lshl_or_b32 v169, v8, 7, v167
	v_lshlrev_b32_e32 v8, 4, v6
	v_or_b32_e32 v7, v7, v2
	s_add_u32 s8, s28, 0xf000000
	v_and_b32_e32 v3, 0x3f0, v3
	v_lshlrev_b32_e32 v171, 2, v7
	v_or_b32_e32 v2, v8, v2
	v_lshlrev_b32_e32 v7, 4, v5
	s_addc_u32 s0, s29, 0
	v_add_u32_e32 v166, 0, v3
	v_lshl_or_b32 v172, v2, 11, v7
	v_lshlrev_b32_e32 v2, 13, v4
	v_lshlrev_b32_e32 v4, 10, v5
	s_and_b32 s9, s0, 0xffff
	v_add_u32_e32 v173, v166, v2
	v_lshl_or_b32 v174, v6, 11, v4
	v_add_u32_e32 v2, 0, v2
	s_mov_b32 s6, 0x10000
	s_mov_b32 s11, 0x20000
	s_brev_b32 s10, -2
	s_cmpk_lg_i32 s34, 0x100
	v_or_b32_e32 v9, v8, v165
	v_add3_u32 v175, v2, v3, s6
	v_add_u32_e32 v2, 0x10000, v174
	s_cselect_b64 s[2:3], -1, 0
	v_lshl_or_b32 v170, v9, 7, v167
	v_cmp_eq_u32_e64 s[0:1], 0, v5
	v_add_u32_e32 v176, v166, v2
	s_mov_b32 s60, s4
	s_mov_b32 s61, s5
	s_mov_b32 s62, s10
	s_mov_b32 s63, s11
	s_mov_b32 s68, s12
	s_mov_b32 s69, s13
	s_mov_b32 s70, s10
	s_mov_b32 s71, s11
	s_mov_b32 s72, s16
	s_mov_b32 s73, s17
	s_mov_b32 s74, s10
	s_mov_b32 s75, s11
	s_mov_b32 s76, s20
	s_mov_b32 s77, s21
	s_mov_b32 s78, s10
	s_mov_b32 s79, s11
	s_mov_b32 s80, s56
	s_mov_b32 s81, s57
	s_mov_b32 s82, s10
	s_mov_b32 s83, s11
	v_and_b32_e32 v177, 63, v164
	v_lshlrev_b32_e32 v177, 4, v177
	v_lshrrev_b32_e32 v169, 6, v164
	v_lshl_or_b32 v169, v169, 12, v177
	v_lshrrev_b32_e32 v170, 7, v164
	v_lshl_or_b32 v170, v170, 11, v177
	s_mov_b32 s35, s92
	s_branch .LBB0_1540

; DEVI void scan_load(ScanFrag& f, __amdgpu_buffer_rsrc_t rq, __amdgpu_buffer_rsrc_t rk, __amdgpu_buffer_rsrc_t rv,
;                     __amdgpu_buffer_rsrc_t rs, int item, int vq, int vk, int vv, int vsc) {
; #pragma unroll
;   for (int tb = 0; tb < 4; ++tb) f.q[tb] = bload(rq, vq, item * 32768 + tb * 8192);
; #pragma unroll
;   for (int rbl = 0; rbl < 2; ++rbl)
; #pragma unroll
;     for (int ks = 0; ks < 2; ++ks) f.kt[rbl][ks] = bload(rk, vk, item * 32768 + rbl * 2048 + ks * 64);
; #pragma unroll
;   for (int sl = 0; sl < 2; ++sl)
; #pragma unroll
;     for (int ks = 0; ks < 2; ++ks) f.v[sl][ks] = bload(rv, vv, item * 65536 + sl * 2048 + ks * 64);
; #pragma unroll
;   for (int ks = 0; ks < 2; ++ks) f.sc[ks] = bload(rs, vsc, item * 8192 + ks * 64);
; }
; DEVI void phase_gla_scan(const Params& p, bf16* shm) {
;     ...
;     scan_load(fa, rq, rk, rv, rs, item0, vq, vk, vv, vsc);
; #pragma unroll
;     for (int rbl = 0; rbl < 2; ++rbl) dv[rbl] = __builtin_amdgcn_raw_buffer_load_b128(rd, vd, item0 * 1024 + rbl * 64, 0);
.LBB0_1544:
	s_lshl_b32 s7, s14, 22
	s_or_b32 s15, s7, 0x2000
	s_lshl_b32 s6, s6, 5
	buffer_load_dwordx4 v[2:5], v168, s[60:63], s7 offen
	buffer_load_dwordx4 v[6:9], v168, s[60:63], s15 offen
	s_or_b32 s15, s7, 0x4000
	s_and_b32 s6, s6, 0x1e0
	s_or_b32 s18, s7, 0x6000
	buffer_load_dwordx4 v[10:13], v168, s[60:63], s15 offen
	buffer_load_dwordx4 v[14:17], v168, s[60:63], s18 offen
	s_or_b32 s15, s7, 0x400
	v_or_b32_e32 v66, s6, v165
	s_lshl_b32 s6, s14, 23
	buffer_load_dwordx4 v[18:21], v169, s[68:71], s7 offen
	buffer_load_dwordx4 v[22:25], v169, s[68:71], s15 offen
	s_or_b32 s15, s7, 0x800
	v_and_b32_e32 v177, 63, v164
	v_lshlrev_b32_e32 v177, 4, v177
	v_and_b32_e32 v178, 0x1e0, v66
	v_lshl_or_b32 v177, v178, 7, v177
	s_or_b32 s18, s7, 0xc00
	buffer_load_dwordx4 v[26:29], v169, s[68:71], s15 offen
	buffer_load_dwordx4 v[30:33], v169, s[68:71], s18 offen
	s_or_b32 s15, s6, 0x400
	buffer_load_dwordx4 v[38:41], v177, s[72:75], s6 offen
	buffer_load_dwordx4 v[42:45], v177, s[72:75], s15 offen
	s_or_b32 s15, s6, 0x800
	s_or_b32 s18, s6, 0xc00
	buffer_load_dwordx4 v[46:49], v177, s[72:75], s15 offen
	buffer_load_dwordx4 v[50:53], v177, s[72:75], s18 offen
	s_lshl_b32 s15, s14, 20
	s_or_b32 s18, s15, 0x400
	buffer_load_dwordx4 v[54:57], v170, s[76:79], s15 offen
	buffer_load_dwordx4 v[58:61], v170, s[76:79], s18 offen
	s_lshl_b32 s18, s14, 17
	s_or_b32 s19, s18, 64
	buffer_load_dwordx4 v[62:65], v171, s[80:83], s18 offen
	buffer_load_dwordx4 v[34:37], v171, s[80:83], s19 offen
	s_lshl_b32 s14, s14, 9
	s_and_b32 s14, s14, 0x600
	v_or3_b32 v66, s14, v172, v66
	v_lshlrev_b32_e32 v178, 1, v66
	s_and_b32 s14, s6, 0xfe000000
	v_mov_b32_e32 v66, 0
	s_or_b32 s36, s14, 0x43000
	s_or_b32 s37, s15, 0x4040
	s_or_b32 s38, s6, 0x20840
	s_or_b32 s39, s7, 0x16000
	s_or_b32 s40, s18, 0x440
	s_mov_b32 s41, 0
	v_mov_b32_e32 v67, v66
	v_mov_b32_e32 v68, v66
	v_mov_b32_e32 v69, v66
	v_mov_b32_e32 v74, v66
	v_mov_b32_e32 v75, v66
	v_mov_b32_e32 v76, v66
	v_mov_b32_e32 v77, v66
	v_mov_b32_e32 v70, v66
	v_mov_b32_e32 v71, v66
	v_mov_b32_e32 v72, v66
	v_mov_b32_e32 v73, v66
	v_mov_b32_e32 v78, v66
	v_mov_b32_e32 v79, v66
	v_mov_b32_e32 v80, v66
	v_mov_b32_e32 v81, v66
	s_branch .LBB0_1546

.LBB0_1546:
	v_cvt_pk_bf16_f32 v82, v66, v67
	v_cvt_pk_bf16_f32 v83, v68, v69
	s_waitcnt vmcnt(1)
	v_pk_mul_f32 v[68:69], v[68:69], v[64:65]
	v_pk_mul_f32 v[66:67], v[66:67], v[62:63]
	v_pk_mul_f32 v[64:65], v[76:77], v[64:65]
	v_pk_mul_f32 v[62:63], v[74:75], v[62:63]
	v_cvt_pk_bf16_f32 v98, v74, v75
	v_cvt_pk_bf16_f32 v99, v76, v77
	v_cvt_pk_bf16_f32 v100, v78, v79
	v_cvt_pk_bf16_f32 v101, v80, v81
	v_mfma_f32_16x16x32_bf16 v[62:65], v[18:21], v[46:49], v[62:65]
	s_add_i32 s6, s39, 0xffff2000
	s_add_i32 s7, s39, 0xffff4000
	buffer_load_dwordx4 v[106:109], v168, s[60:63], s6 offen
	buffer_load_dwordx4 v[110:113], v168, s[60:63], s7 offen
	v_mfma_f32_16x16x32_bf16 v[154:157], v[2:5], v[98:101], 0
	s_add_i32 s7, s39, 0xffff6000
	v_cvt_pk_bf16_f32 v84, v70, v71
	v_cvt_pk_bf16_f32 v85, v72, v73
	v_mfma_f32_16x16x32_bf16 v[158:161], v[6:9], v[98:101], 0
	s_add_i32 s14, s39, 0xffff8000
	buffer_load_dwordx4 v[122:125], v168, s[60:63], s7 offen
	buffer_load_dwordx4 v[126:129], v168, s[60:63], s14 offen
	s_add_i32 s7, s39, 0xffff2400
	v_mfma_f32_16x16x32_bf16 v[180:183], v[10:13], v[98:101], 0
	buffer_load_dwordx4 v[90:93], v169, s[68:71], s6 offen
	buffer_load_dwordx4 v[94:97], v169, s[68:71], s7 offen
	s_add_i32 s6, s39, 0xffff2800
	s_add_i32 s7, s39, 0xffff2c00
	v_mfma_f32_16x16x32_bf16 v[184:187], v[14:17], v[98:101], 0
	v_cndmask_b32_e64 v101, v49, v41, s[0:1]
	v_cndmask_b32_e64 v100, v48, v40, s[0:1]
	v_cndmask_b32_e64 v99, v47, v39, s[0:1]
	v_cndmask_b32_e64 v98, v46, v38, s[0:1]
	v_mfma_f32_16x16x32_bf16 v[74:77], v[22:25], v[50:53], v[62:65]
	v_cndmask_b32_e64 v105, v53, v45, s[0:1]
	v_cndmask_b32_e64 v104, v52, v44, s[0:1]
	v_cndmask_b32_e64 v103, v51, v43, s[0:1]
	v_mfma_f32_16x16x32_bf16 v[98:101], v[54:57], v[98:101], 0
	s_waitcnt vmcnt(6)
	v_pk_mul_f32 v[64:65], v[72:73], v[36:37]
	v_pk_mul_f32 v[62:63], v[70:71], v[34:35]
	v_cndmask_b32_e64 v102, v50, v42, s[0:1]
	v_mfma_f32_16x16x32_bf16 v[138:141], v[2:5], v[82:85], 0
	v_mul_f32_e64 v80, v80, v36
	v_mul_f32_e64 v81, v81, v37
	v_pk_mul_f32 v[78:79], v[78:79], v[34:35]
	v_mfma_f32_16x16x32_bf16 v[142:145], v[6:9], v[82:85], 0
	v_mfma_f32_16x16x32_bf16 v[146:149], v[10:13], v[82:85], 0
	v_mfma_f32_16x16x32_bf16 v[150:153], v[14:17], v[82:85], 0
	buffer_load_dwordx4 v[86:89], v169, s[68:71], s6 offen
	buffer_load_dwordx4 v[82:85], v169, s[68:71], s7 offen
	s_add_i32 s6, s38, 0xfffef7c0
	s_add_i32 s7, s38, 0xfffefbc0
	v_mfma_f32_16x16x32_bf16 v[62:65], v[26:29], v[38:41], v[62:65]
	v_mfma_f32_16x16x32_bf16 v[188:191], v[58:61], v[102:105], v[98:101]
	buffer_load_dwordx4 v[102:105], v177, s[72:75], s6 offen
	s_nop 1
	buffer_load_dwordx4 v[98:101], v177, s[72:75], s7 offen
	s_add_i32 s6, s38, 0xfffeffc0
	s_add_i32 s7, s38, 0xffff03c0
	buffer_load_dwordx4 v[118:121], v177, s[72:75], s6 offen
	buffer_load_dwordx4 v[114:117], v177, s[72:75], s7 offen
	s_add_i32 s6, s37, 0xffffdfc0
	s_add_i32 s7, s37, 0xffffe3c0
	buffer_load_dwordx4 v[134:137], v170, s[76:79], s6 offen
	buffer_load_dwordx4 v[130:133], v170, s[76:79], s7 offen
	s_sub_i32 s6, s40, 64
	v_mfma_f32_16x16x32_bf16 v[70:73], v[30:33], v[42:45], v[62:65]
	s_nop 2
	buffer_load_dwordx4 v[62:65], v171, s[80:83], s6 offen
	buffer_load_dwordx4 v[34:37], v171, s[80:83], s40 offen
	ds_write_b128 v173, v[138:141]
	ds_write_b128 v173, v[154:157] offset:1024
	ds_write_b128 v173, v[142:145] offset:2048
	ds_write_b128 v173, v[158:161] offset:3072
	ds_write_b128 v173, v[146:149] offset:4096
	ds_write_b128 v173, v[180:183] offset:5120
	ds_write_b128 v173, v[150:153] offset:6144
	ds_write_b128 v173, v[184:187] offset:7168
	s_waitcnt lgkmcnt(0)
	s_barrier
; DEVI void scan_load(ScanFrag& f, __amdgpu_buffer_rsrc_t rq, __amdgpu_buffer_rsrc_t rk, __amdgpu_buffer_rsrc_t rv,
;                     __amdgpu_buffer_rsrc_t rs, int item, int vq, int vk, int vv, int vsc) {
; #pragma unroll
;   for (int tb = 0; tb < 4; ++tb) f.q[tb] = bload(rq, vq, item * 32768 + tb * 8192);
; #pragma unroll
;   for (int rbl = 0; rbl < 2; ++rbl)
; #pragma unroll
;     for (int ks = 0; ks < 2; ++ks) f.kt[rbl][ks] = bload(rk, vk, item * 32768 + rbl * 2048 + ks * 64);
; #pragma unroll
;   for (int sl = 0; sl < 2; ++sl)
; #pragma unroll
;     for (int ks = 0; ks < 2; ++ks) f.v[sl][ks] = bload(rv, vv, item * 65536 + sl * 2048 + ks * 64);
; #pragma unroll
;   for (int ks = 0; ks < 2; ++ks) f.sc[ks] = bload(rs, vsc, item * 8192 + ks * 64);
; }
	v_add_u32_e32 v146, v166, v174
	ds_read_b128 v[138:141], v146
	ds_read_b128 v[142:145], v146 offset:8192
	v_mfma_f32_16x16x32_bf16 v[66:69], v[18:21], v[38:41], v[66:69]
	s_add_i32 s6, s36, 0xfffbd000
	s_waitcnt lgkmcnt(1)
	v_add_f32_e32 v138, v188, v138
	v_add_f32_e32 v147, v189, v139
	v_add_f32_e32 v148, v190, v140
	v_add_f32_e32 v149, v191, v141
	s_waitcnt lgkmcnt(0)
	v_add_f32_e32 v150, v138, v142
	ds_read_b128 v[138:141], v146 offset:16384
	v_add_f32_e32 v147, v147, v143
	v_add_f32_e32 v148, v148, v144
	v_add_f32_e32 v149, v149, v145
	ds_read_b128 v[142:145], v146 offset:24576
	s_waitcnt lgkmcnt(1)
	v_add_f32_e32 v138, v150, v138
	v_add_f32_e32 v147, v147, v139
	v_add_f32_e32 v148, v148, v140
	v_add_f32_e32 v149, v149, v141
	s_waitcnt lgkmcnt(0)
	v_add_f32_e32 v150, v138, v142
	ds_read_b128 v[138:141], v146 offset:32768
	v_add_f32_e32 v147, v147, v143
	v_add_f32_e32 v148, v148, v144
	v_add_f32_e32 v149, v149, v145
	ds_read_b128 v[142:145], v146 offset:40960
	s_waitcnt lgkmcnt(1)
	v_add_f32_e32 v138, v150, v138
	v_add_f32_e32 v147, v147, v139
	v_add_f32_e32 v148, v148, v140
	v_add_f32_e32 v149, v149, v141
	s_waitcnt lgkmcnt(0)
	v_add_f32_e32 v150, v138, v142
	ds_read_b128 v[138:141], v146 offset:49152
	v_add_f32_e32 v147, v147, v143
	v_add_f32_e32 v148, v148, v144
	v_add_f32_e32 v149, v149, v145
	ds_read_b128 v[142:145], v146 offset:57344
	s_waitcnt lgkmcnt(1)
	v_add_f32_e32 v138, v150, v138
	v_add_f32_e32 v139, v147, v139
	v_mfma_f32_16x16x32_bf16 v[78:81], v[26:29], v[46:49], v[78:81]
	v_add_f32_e32 v140, v148, v140
	s_waitcnt lgkmcnt(0)
	v_add_f32_e32 v138, v138, v142
	v_add_f32_e32 v139, v139, v143
	v_cvt_pk_bf16_f32 v138, v138, s0
	v_add_f32_e32 v140, v140, v144
	buffer_store_short v138, v178, s[8:11], s6 offen
	v_cvt_pk_bf16_f32 v138, v139, s0
	s_add_i32 s6, s36, 0xfffbe000
	buffer_store_short v138, v178, s[8:11], s6 offen
	v_cvt_pk_bf16_f32 v138, v140, s0
	s_add_i32 s6, s36, 0xfffbf000
	buffer_store_short v138, v178, s[8:11], s6 offen
	s_add_i32 s6, s36, 0xfffc0000
	v_mfma_f32_16x16x32_bf16 v[66:69], v[22:25], v[42:45], v[66:69]
	s_cmpk_lt_u32 s41, 0x7e
	v_add_f32_e32 v141, v149, v141
	s_cselect_b64 s[58:59], -1, 0
	v_mfma_f32_16x16x32_bf16 v[78:81], v[30:33], v[50:53], v[78:81]
	s_cmpk_gt_u32 s41, 0x7d
	v_add_f32_e32 v141, v141, v145
	s_cselect_b64 s[52:53], -1, 0
	v_cvt_pk_bf16_f32 v138, v141, s0
	s_and_b64 vcc, exec, s[52:53]
	buffer_store_short v138, v178, s[8:11], s6 offen
	s_cbranch_vccnz .LBB0_1548
	s_add_i32 s18, s39, 0xffffa000
	s_mov_b32 s6, s10
	s_mov_b32 s7, s11
	s_add_i32 s14, s39, 0xffffc000
	buffer_load_dwordx4 v[2:5], v168, s[4:7], s18 offen
	buffer_load_dwordx4 v[6:9], v168, s[4:7], s14 offen
	s_add_i32 s14, s39, 0xffffe000
	buffer_load_dwordx4 v[10:13], v168, s[4:7], s14 offen
	buffer_load_dwordx4 v[14:17], v168, s[4:7], s39 offen
	s_mov_b32 s14, s10
	s_mov_b32 s15, s11
	s_add_i32 s6, s39, 0xffffa400
	buffer_load_dwordx4 v[18:21], v169, s[12:15], s18 offen
	buffer_load_dwordx4 v[22:25], v169, s[12:15], s6 offen
	s_add_i32 s6, s39, 0xffffa800
	s_add_i32 s7, s39, 0xffffac00
	buffer_load_dwordx4 v[26:29], v169, s[12:15], s6 offen
	buffer_load_dwordx4 v[30:33], v169, s[12:15], s7 offen
	s_add_i32 s6, s38, 0xfffff7c0
	s_mov_b32 s18, s10
	s_mov_b32 s19, s11
	s_add_i32 s7, s38, 0xfffffbc0
	buffer_load_dwordx4 v[38:41], v177, s[16:19], s6 offen
	buffer_load_dwordx4 v[42:45], v177, s[16:19], s7 offen
	s_sub_i32 s6, s38, 64
	buffer_load_dwordx4 v[46:49], v177, s[16:19], s6 offen
	s_add_i32 s7, s38, 0x3c0
	buffer_load_dwordx4 v[50:53], v177, s[16:19], s7 offen
	s_sub_i32 s6, s37, 64
	s_mov_b32 s22, s10
	s_mov_b32 s23, s11
	buffer_load_dwordx4 v[54:57], v170, s[20:23], s6 offen
	s_add_i32 s7, s37, 0x3c0
	buffer_load_dwordx4 v[58:61], v170, s[20:23], s7 offen
